# T1 (MLA) loop re-cut: barrier after QK, K-tile LDS writes in PV MFMA gaps, V-tile writes in next QK gaps (prologue keeps V0 in staging regs, peeled last iteration writes V + barrier); removes the expo
# speedup vs baseline: 1.0353x; 1.0042x over previous
; template <int DQK, int DV, int TYPE>
; DI void attn_item(int layer, int qt, int head, char* lds, const Params& P) {
;     ...
;   for (int map = 0; map < NMAPS; ++map) {
;     const u16* Kb = Kp + map * 64;
;     const u16* Qp;
;     if (TYPE == 0) Qp = reinterpret_cast<const u16*>(ws + O_QA) + (long)qrow * 1024 + head * 128 + map * 64;
;     else if (TYPE == 1) Qp = reinterpret_cast<const u16*>(ws + O_QC) + (long)qrow * 1536 + head * 192;
;     else Qp = reinterpret_cast<const u16*>(ws + O_QB) + (long)qrow * 1024 + head * 64;
;     constexpr int NQR = NS > 6 ? 6 : NS;
;     bf16x8 qf[NQR];
; #pragma unroll
;     for (int s = 0; s < NQR; ++s) qf[s] = *GPC(bf16x8, Qp + 16 * s + 8 * h);
;     char* qpark = lds + 40960 + tid * 16;
; #pragma unroll
;     for (int s = NQR; s < NS; ++s) *reinterpret_cast<bf16x8*>(qpark + (s - NQR) * 4096) = *GPC(bf16x8, Qp + 16 * s + 8 * h);
;     float m_run, l_run;
;     if (TYPE == 2) { m_run = P.in[12][layer * 16 + head] * (1.f / SCALE); l_run = 1.f; }
;     else { m_run = -1e30f; l_run = 0.f; }
;     f32x16 oacc[NDV];
; #pragma unroll
;     for (int d = 0; d < NDV; ++d)
; #pragma unroll
;       for (int i = 0; i < 16; ++i) oacc[d][i] = 0.f;
;     ...
;     ATT_GLOAD(TILE_OF(0));
;     ATT_SSTORE(lds);
;     if constexpr (DB) { if (1 < NT) { ATT_GLOAD(TILE_OF(1)); } }
;     __syncthreads();
.LBB0_358:
	s_andn2_b64 vcc, exec, s[0:1]
	s_cbranch_vccnz .LBB0_367
	s_lshl_b32 s0, s29, 4
	v_mov_b32_e32 v3, v218
	s_and_b32 s0, s0, 0x7f80
	s_addk_i32 s0, 0xc000
	v_and_b32_e32 v10, 31, v3
	v_ashrrev_i32_e32 v0, 1, v3
	v_and_b32_e32 v0, 0xffffffe0, v0
	s_waitcnt vmcnt(0)
	v_or_b32_e32 v4, s0, v10
	v_add_u32_e32 v196, v4, v0
	v_and_b32_e32 v4, 15, v3
	v_lshrrev_b32_e32 v2, 5, v3
	v_ashrrev_i32_e32 v0, 4, v3
	v_lshlrev_b32_e32 v5, 4, v4
	s_movk_i32 s31, 0x180
	v_lshl_or_b32 v16, v0, 11, v5
	v_mul_lo_u32 v6, v0, s31
	v_bitop3_b32 v0, v2, v4, 7 bitop3:0x6c
	v_and_b32_e32 v4, 7, v3
	v_bfe_u32 v8, v3, 4, 3
	v_lshlrev_b32_e32 v7, 4, v0
	v_ashrrev_i32_e32 v0, 3, v3
	v_bitop3_b32 v8, v4, v8, 16 bitop3:0x36
	s_mov_b32 s16, 0x8200
	v_readfirstlane_b32 s12, v174
	v_readfirstlane_b32 s13, v175
	v_lshrrev_b32_e32 v5, 4, v3
	v_lshlrev_b32_e32 v12, 4, v8
	v_lshlrev_b32_e32 v4, 4, v4
	v_mul_lo_u32 v8, v0, s16
	v_lshlrev_b32_e32 v13, 7, v0
	v_mul_lo_u32 v11, v0, s31
	v_or_b32_e32 v198, v4, v8
	v_or_b32_e32 v200, v13, v4
	v_bitop3_b32 v0, v5, v3, 7 bitop3:0x28
	v_mov_b64_e32 v[4:5], s[12:13]
	s_movk_i32 s16, 0xc00
	s_and_b32 s18, s29, 7
	v_mad_i64_i32 v[4:5], s[16:17], v196, s16, v[4:5]
	v_bfe_u32 v190, v3, 5, 1
	s_mul_i32 s16, s18, 0x180
	s_mov_b32 s17, s35
	v_lshlrev_b32_e32 v14, 4, v0
	v_lshl_add_u64 v[4:5], v[4:5], 0, s[16:17]
	v_lshlrev_b32_e32 v0, 4, v190
	v_lshl_add_u64 v[4:5], v[4:5], 0, v[0:1]
	s_mov_b64 s[16:17], 0x1275a100
	v_add_u32_e32 v6, 0, v6
	v_mad_u32_u24 v228, v10, s31, 0
	s_mov_b32 s31, 0x1275a000
	v_lshl_add_u64 v[8:9], v[4:5], 0, s[16:17]
	v_add_u32_e32 v225, v6, v7
	v_add_u32_e32 v6, 0, v11
	v_add_co_u32_e32 v4, vcc, s31, v4
	v_add_u32_e32 v226, v6, v12
	v_add_u32_e32 v6, 0, v13
	v_addc_co_u32_e32 v5, vcc, 0, v5, vcc
	v_add_u32_e32 v227, v6, v14
	global_load_dwordx4 v[118:121], v[4:5], off offset:256
	global_load_dwordx4 v[114:117], v[8:9], off offset:32
	global_load_dwordx4 v[110:113], v[8:9], off offset:64
	global_load_dwordx4 v[106:109], v[8:9], off offset:96
	global_load_dwordx4 v[102:105], v[8:9], off offset:128
	global_load_dwordx4 v[98:101], v[8:9], off offset:160
	global_load_dwordx4 v[4:7], v[8:9], off offset:192
	v_lshlrev_b32_e32 v15, 4, v3
	v_add_u32_e32 v194, 0, v15
	s_lshl_b32 s2, s18, 7
	s_lshl_b32 s0, s18, 8
	s_add_u32 s4, s12, s0
	s_addc_u32 s5, s13, 0
	s_add_u32 s6, s4, 0x1581a100
	s_addc_u32 s7, s5, 0
	s_mul_i32 s0, s18, 0x410000
	s_add_u32 s14, s12, s0
	s_addc_u32 s20, s13, 0
	s_add_u32 s0, s14, 0x1789a100
	s_addc_u32 s1, s20, 0
	s_add_u32 s18, s4, 0x1582a100
	s_addc_u32 s19, s5, 0
	s_add_u32 s16, s14, 0x17aa2100
	s_addc_u32 s17, s20, 0
	s_add_u32 s36, s12, 0x12552100
	s_addc_u32 s37, s13, 0
	s_add_u32 s48, s4, 0x15822100
	s_addc_u32 s49, s5, 0
	s_add_u32 s50, s14, 0x1799e100
	s_addc_u32 s51, s20, 0
	s_add_u32 s4, s4, 0x15832100
	s_addc_u32 s5, s5, 0
	s_add_u32 s52, s14, 0x17ba6100
	s_addc_u32 s53, s20, 0
	s_add_u32 s54, s12, 0x12553100
	v_mov_b32_e32 v0, v16
	s_addc_u32 s55, s13, 0
	v_bfe_u32 v3, v3, 1, 3
	v_bitop3_b32 v2, v2, v3, 1 bitop3:0x6c
	v_lshlrev_b32_e32 v239, 4, v2
	v_bitop3_b32 v2, v190, v3, 2 bitop3:0x36
	v_lshlrev_b32_e32 v240, 4, v2
	v_bitop3_b32 v2, v190, v3, 4 bitop3:0x36
	v_lshlrev_b32_e32 v241, 4, v2
	v_bitop3_b32 v2, v190, v3, 6 bitop3:0x36
	v_lshlrev_b32_e32 v242, 4, v2
	v_bitop3_b32 v2, v190, v3, 8 bitop3:0x36
	v_ashrrev_i32_e32 v197, 31, v196
	v_mov_b32_e32 v201, v1
	v_mov_b32_e32 v199, v1
	s_mov_b32 s20, 0x800000
	v_mov_b32_e32 v251, 0
	v_mov_b32_e32 v248, 0xf149f2ca
	s_waitcnt vmcnt(0)
	ds_write_b128 v194, v[4:7] offset:40960
	global_load_dwordx4 v[4:7], v[8:9], off offset:224
	s_waitcnt vmcnt(0)
	ds_write_b128 v194, v[4:7] offset:45056
	global_load_dwordx4 v[4:7], v[8:9], off offset:256
	s_waitcnt vmcnt(0)
	ds_write_b128 v194, v[4:7] offset:49152
	global_load_dwordx4 v[4:7], v[8:9], off offset:288
	s_waitcnt vmcnt(0)
	ds_write_b128 v194, v[4:7] offset:53248
	global_load_dwordx4 v[4:7], v[8:9], off offset:320
	s_waitcnt vmcnt(0)
	ds_write_b128 v194, v[4:7] offset:57344
	global_load_dwordx4 v[4:7], v[8:9], off offset:352
	s_waitcnt vmcnt(0)
	ds_write_b128 v194, v[4:7] offset:61440
	v_lshlrev_b32_e32 v4, 8, v10
	v_sub_u32_e32 v232, v228, v4
	global_load_dwordx4 v[4:7], v16, s[6:7]
	global_load_dwordx4 v[8:11], v16, s[48:49]
	global_load_dwordx4 v[12:15], v16, s[18:19]
	s_nop 0
	global_load_dwordx4 v[16:19], v16, s[4:5]
	s_nop 0
	global_load_dwordx4 v[20:23], v200, s[36:37]
	global_load_dwordx4 v[24:27], v200, s[54:55]
	global_load_dwordx4 v[146:149], v198, s[0:1]
	global_load_dwordx4 v[150:153], v198, s[50:51]
	global_load_dwordx4 v[154:157], v198, s[16:17]
	global_load_dwordx4 v[158:161], v198, s[52:53]
	s_movk_i32 s52, 0x70
	v_readlane_b32 s53, v254, 39
	s_mov_b64 s[0:1], 0
	s_waitcnt vmcnt(0)
	ds_write_b128 v225, v[4:7]
	ds_write_b128 v225, v[8:11] offset:6144
	ds_write_b128 v225, v[12:15] offset:12288
	ds_write_b128 v225, v[16:19] offset:18432
	ds_write_b128 v226, v[20:23]
	ds_write_b128 v226, v[24:27] offset:12288
	v_lshlrev_b32_e32 v18, 4, v2
	v_bitop3_b32 v2, v190, v3, 10 bitop3:0x36
	v_lshlrev_b32_e32 v19, 4, v2
	v_bitop3_b32 v2, v190, v3, 12 bitop3:0x36
	v_lshlrev_b32_e32 v20, 4, v2
	v_bitop3_b32 v2, v190, v3, 14 bitop3:0x36
	v_lshlrev_b32_e32 v21, 4, v2
	v_bitop3_b32 v2, v190, v3, 16 bitop3:0x36
	v_lshlrev_b32_e32 v22, 4, v2
	v_bitop3_b32 v2, v190, v3, 18 bitop3:0x36
	v_lshlrev_b32_e32 v23, 4, v2
	v_bitop3_b32 v2, v190, v3, 20 bitop3:0x36
	v_lshlrev_b32_e32 v24, 4, v2
	v_bitop3_b32 v2, v190, v3, 22 bitop3:0x36
	v_lshlrev_b32_e32 v25, 4, v2
	v_mov_b32_e32 v16, v1
	v_mov_b32_e32 v17, v1
	v_mov_b32_e32 v2, v1
	v_mov_b32_e32 v3, v1
	v_mov_b32_e32 v4, v1
	v_mov_b32_e32 v5, v1
	v_mov_b32_e32 v6, v1
	v_mov_b32_e32 v7, v1
	v_mov_b32_e32 v8, v1
	v_mov_b32_e32 v9, v1
	v_mov_b32_e32 v10, v1
	v_mov_b32_e32 v11, v1
	v_mov_b32_e32 v12, v1
	v_mov_b32_e32 v13, v1
	v_mov_b32_e32 v14, v1
	v_mov_b32_e32 v15, v1
	v_add_u32_e32 v244, v228, v18
	v_add_u32_e32 v243, v228, v19
	v_add_u32_e32 v238, v228, v20
	v_add_u32_e32 v237, v228, v21
	v_add_u32_e32 v236, v228, v22
	v_add_u32_e32 v235, v228, v23
	v_add_u32_e32 v234, v228, v24
	v_add_u32_e32 v233, v228, v25
	v_mov_b64_e32 v[32:33], v[16:17]
	v_mov_b64_e32 v[48:49], v[16:17]
	v_mov_b64_e32 v[64:65], v[16:17]
	v_mov_b64_e32 v[30:31], v[14:15]
	v_mov_b64_e32 v[28:29], v[12:13]
	v_mov_b64_e32 v[26:27], v[10:11]
	v_mov_b64_e32 v[24:25], v[8:9]
	v_mov_b64_e32 v[22:23], v[6:7]
	v_mov_b64_e32 v[20:21], v[4:5]
	v_mov_b64_e32 v[18:19], v[2:3]
	v_mov_b64_e32 v[46:47], v[14:15]
	v_mov_b64_e32 v[44:45], v[12:13]
	v_mov_b64_e32 v[42:43], v[10:11]
	v_mov_b64_e32 v[40:41], v[8:9]
	v_mov_b64_e32 v[38:39], v[6:7]
	v_mov_b64_e32 v[36:37], v[4:5]
	v_mov_b64_e32 v[34:35], v[2:3]
	v_mov_b64_e32 v[62:63], v[14:15]
	v_mov_b64_e32 v[60:61], v[12:13]
	v_mov_b64_e32 v[58:59], v[10:11]
	v_mov_b64_e32 v[56:57], v[8:9]
	v_mov_b64_e32 v[54:55], v[6:7]
	v_mov_b64_e32 v[52:53], v[4:5]
	v_mov_b64_e32 v[50:51], v[2:3]
	s_waitcnt lgkmcnt(0)
	s_barrier
; #define MFMA(a, b, c) __builtin_amdgcn_mfma_f32_32x32x16_bf16((a), (b), (c), 0, 0, 0)
; template <int DQK, int DV, int TYPE>
; DI void attn_item(int layer, int qt, int head, char* lds, const Params& P) {
;     ...
;     for (int j = 0; j < NT; ++j) {
;       const int tile = TILE_OF(j);
;       const char* sb = lds + (DB ? (j & 1) * STAGE : 0);
;       constexpr int KD = 2, KRING = 3;
;       bf16x8 kr0[KRING], kr1[KRING];
;     ...
; #pragma unroll
;       for (int s = 0; s < KD; ++s) KFR(s, s)
;       __builtin_amdgcn_sched_barrier(0);
;       if constexpr (DB) {
;         char* sn = lds + ((j + 1) & 1) * STAGE;
;         if (j + 1 < NT) { ATT_SSTORE(sn); }
;         if (j + 2 < NT) { ATT_GLOAD(TILE_OF(j + 2)); }
;       } else {
;         if (j + 1 < NT) { ATT_GLOAD(TILE_OF(j + 1)); }
;       }
;       f32x16 s0, s1;
; #pragma unroll
;       for (int i = 0; i < 16; ++i) { s0[i] = 0.f; s1[i] = 0.f; }
;       {
; #pragma unroll
;         for (int s = 0; s < NS; ++s) {
;           if (s + KD < NS) KFR(s + KD, (s + KD) % KRING)
;           bf16x8 qs;
;           if constexpr (NS > NQR) { if (s < NQR) qs = qf[s < NQR ? s : 0]; else qs = *reinterpret_cast<const bf16x8*>(qpark + (s - NQR) * 4096); }
;           else qs = qf[s];
;           s0 = MFMA(kr0[s % KRING], qs, s0);
;           s1 = MFMA(kr1[s % KRING], qs, s1);
;           __builtin_amdgcn_sched_barrier(0);
;         }
;     ...
;       }
.LBB0_360:
	v_add_u32_e32 v246, v228, v239
	v_add_u32_e32 v247, v228, v240
	ds_read_b128 v[66:69], v246
	ds_read_b128 v[70:73], v246 offset:12288
	ds_read_b128 v[162:165], v247
	ds_read_b128 v[166:169], v247 offset:12288
	s_waitcnt lgkmcnt(3)
	v_mfma_f32_32x32x16_bf16 v[82:97], v[66:69], v[118:121], 0
	v_add_u32_e32 v249, v228, v241
	ds_read_b128 v[170:173], v249
	ds_read_b128 v[202:205], v249 offset:12288
	s_waitcnt lgkmcnt(4)
	v_mfma_f32_32x32x16_bf16 v[66:81], v[70:73], v[118:121], 0
	s_waitcnt vmcnt(0)
	ds_write_b128 v227, v[146:149] offset:24576
	s_add_u32 s6, s12, s46
	s_addc_u32 s7, s13, s47
	s_add_u32 s4, s6, 0x1583a100
	s_addc_u32 s5, s7, 0
	global_load_dwordx4 v[122:125], v0, s[4:5]
	s_waitcnt lgkmcnt(4)
	v_mfma_f32_32x32x16_bf16 v[82:97], v[162:165], v[114:117], v[82:97]
	v_add_u32_e32 v250, v228, v242
	ds_read_b128 v[162:165], v250
	ds_read_b128 v[206:209], v250 offset:12288
	s_waitcnt lgkmcnt(5)
	v_mfma_f32_32x32x16_bf16 v[66:81], v[166:169], v[114:117], v[66:81]
	ds_write_b128 v227, v[150:153] offset:28672
	s_add_u32 s4, s6, 0x15842100
	s_addc_u32 s5, s7, 0
	global_load_dwordx4 v[126:129], v0, s[4:5]
	s_waitcnt lgkmcnt(5)
	v_mfma_f32_32x32x16_bf16 v[82:97], v[170:173], v[110:113], v[82:97]
	ds_read_b128 v[166:169], v244
	ds_read_b128 v[170:173], v244 offset:12288
	s_waitcnt lgkmcnt(6)
	v_mfma_f32_32x32x16_bf16 v[66:81], v[202:205], v[110:113], v[66:81]
	ds_write_b128 v227, v[154:157] offset:32768
	s_add_u32 s4, s6, 0x1584a100
	s_addc_u32 s5, s7, 0
	global_load_dwordx4 v[130:133], v0, s[4:5]
	s_waitcnt lgkmcnt(5)
	v_mfma_f32_32x32x16_bf16 v[82:97], v[162:165], v[106:109], v[82:97]
	ds_read_b128 v[162:165], v243
	ds_read_b128 v[202:205], v243 offset:12288
	s_waitcnt lgkmcnt(6)
	v_mfma_f32_32x32x16_bf16 v[66:81], v[206:209], v[106:109], v[66:81]
	ds_write_b128 v227, v[158:161] offset:36864
	s_add_u32 s4, s6, 0x15852100
	s_addc_u32 s5, s7, 0
	s_add_u32 s6, s12, s0
	s_addc_u32 s7, s13, s1
	global_load_dwordx4 v[134:137], v0, s[4:5]
	s_waitcnt lgkmcnt(5)
	v_mfma_f32_32x32x16_bf16 v[82:97], v[166:169], v[102:105], v[82:97]
	ds_read_b128 v[166:169], v238
	ds_read_b128 v[206:209], v238 offset:12288
	s_waitcnt lgkmcnt(6)
	v_mfma_f32_32x32x16_bf16 v[66:81], v[170:173], v[102:105], v[66:81]
	s_add_u32 s4, s6, 0x12554100
	s_addc_u32 s5, s7, 0
	global_load_dwordx4 v[138:141], v200, s[4:5]
	ds_read_b128 v[214:217], v194 offset:40960
	s_waitcnt lgkmcnt(5)
	v_mfma_f32_32x32x16_bf16 v[82:97], v[162:165], v[98:101], v[82:97]
	ds_read_b128 v[162:165], v237
	ds_read_b128 v[170:173], v237 offset:12288
	s_waitcnt lgkmcnt(6)
	v_mfma_f32_32x32x16_bf16 v[66:81], v[202:205], v[98:101], v[66:81]
	s_add_u32 s4, s6, 0x12555100
	s_addc_u32 s5, s7, 0
	s_add_u32 s6, s12, s44
	s_addc_u32 s7, s13, s45
	global_load_dwordx4 v[142:145], v200, s[4:5]
	ds_read_b128 v[210:213], v194 offset:45056
	ds_read_b128 v[202:205], v236
	s_waitcnt lgkmcnt(4)
	v_mfma_f32_32x32x16_bf16 v[82:97], v[166:169], v[214:217], v[82:97]
	ds_read_b128 v[166:169], v236 offset:12288
	v_mfma_f32_32x32x16_bf16 v[66:81], v[206:209], v[214:217], v[66:81]
	s_add_u32 s4, s6, 0x1789a180
	s_addc_u32 s5, s7, 0
	global_load_dwordx4 v[146:149], v198, s[4:5]
	ds_read_b128 v[214:217], v194 offset:49152
	ds_read_b128 v[206:209], v235
	s_waitcnt lgkmcnt(4)
	v_mfma_f32_32x32x16_bf16 v[82:97], v[162:165], v[210:213], v[82:97]
	ds_read_b128 v[162:165], v235 offset:12288
	v_mfma_f32_32x32x16_bf16 v[66:81], v[170:173], v[210:213], v[66:81]
	s_add_u32 s4, s6, 0x1799e180
	s_addc_u32 s5, s7, 0
	global_load_dwordx4 v[150:153], v198, s[4:5]
	ds_read_b128 v[210:213], v194 offset:53248
	ds_read_b128 v[170:173], v234
	s_waitcnt lgkmcnt(4)
	v_mfma_f32_32x32x16_bf16 v[82:97], v[202:205], v[214:217], v[82:97]
	ds_read_b128 v[202:205], v234 offset:12288
	v_mfma_f32_32x32x16_bf16 v[66:81], v[166:169], v[214:217], v[66:81]
	s_add_u32 s4, s6, 0x17aa2180
	s_addc_u32 s5, s7, 0
	global_load_dwordx4 v[154:157], v198, s[4:5]
	ds_read_b128 v[214:217], v194 offset:57344
	ds_read_b128 v[166:169], v233
	s_waitcnt lgkmcnt(4)
	v_mfma_f32_32x32x16_bf16 v[82:97], v[206:209], v[210:213], v[82:97]
	ds_read_b128 v[206:209], v233 offset:12288
	v_mfma_f32_32x32x16_bf16 v[66:81], v[162:165], v[210:213], v[66:81]
	s_add_u32 s4, s6, 0x17ba6180
	s_addc_u32 s5, s7, 0
	global_load_dwordx4 v[158:161], v198, s[4:5]
	ds_read_b128 v[210:213], v194 offset:61440
	s_waitcnt lgkmcnt(3)
	v_mfma_f32_32x32x16_bf16 v[82:97], v[170:173], v[214:217], v[82:97]
	v_mfma_f32_32x32x16_bf16 v[66:81], v[202:205], v[214:217], v[66:81]
	s_waitcnt lgkmcnt(0)
	v_mfma_f32_32x32x16_bf16 v[82:97], v[166:169], v[210:213], v[82:97]
	v_add_u32_e32 v231, v232, v239
	v_add_u32_e32 v229, v232, v241
	v_add_u32_e32 v230, v232, v240
	v_mfma_f32_32x32x16_bf16 v[66:81], v[206:209], v[210:213], v[66:81]
	s_barrier
; template <int DQK, int DV, int TYPE>
; DI void attn_item(int layer, int qt, int head, char* lds, const Params& P) {
;     ...
;       const char* vb0 = sb + VOFF + r * 128;
;     ...
;       constexpr int VD = 3;
;       bf16x8 vr[8];
; #pragma unroll
;       for (int g = 0; g < VD; ++g) vr[g] = VFRAG(g >> 2, g & 3);
;       if (TYPE == 2 && latent && j < na) {
;         const int kb0 = tile * 64 - qrow;
; #pragma unroll
;         for (int i = 0; i < 16; ++i) {
;           const int d0 = kb0 + crow(i, h), d1 = d0 + 32;
;           if (d0 > 128 || d0 < -128) s0[i] = -1e30f;
;           if (d1 > 128 || d1 < -128) s1[i] = -1e30f;
;         }
;       }
;       const float tm0 = vmax3w(s0[0], s0[1], s0[2], s1[0]);
;       const float tm1 = vmax3d(s0[3], s0[4], s0[5], tm0), tm2 = vmax3d(s0[6], s0[7], s0[8], tm0), tm3 = vmax3d(s0[9], s0[10], s0[11], tm0);
;       const float tm4 = vmax3d(s0[12], s0[13], s0[14], tm0);
;       const float tm5 = vmax3d4(s1[0], s1[1], s1[2], tm1, tm2, tm3, tm4), tm6 = vmax3d(s1[3], s1[4], s1[5], tm5), tm7 = vmax3d(s1[6], s1[7], s1[8], tm5);
;       const float tm8 = vmax3d(s1[9], s1[10], s1[11], tm5), tm9 = vmax3d(s1[12], s1[13], s1[14], tm5), tma = vmax3d(s0[15], s1[15], tm0, tm5), tmb = vmax3(tm1, tm2, tm3);
;       const float tmc = vmax3(tm4, tm5, tm6), tmd = vmax3(tm7, tm8, tm9);
;       float tmax = xhalf_max(vmax3(vmax3(tma, tmb, tmc), tmd, tmd));
;       const float mnew = fmaxf(m_run, tmax);
;       const float alpha = __builtin_amdgcn_exp2f((m_run - mnew) * C);
;       m_run = mnew;
;       const float mc = -mnew * C;
;       float pa = 0.f, pb = 0.f, pc = 0.f, pd = 0.f;
; #pragma unroll
;       for (int i = 0; i < 16; i += 2) {
;         s0[i] = __builtin_amdgcn_exp2f(fmaf(s0[i], C, mc)); pa += s0[i];
;         s0[i + 1] = __builtin_amdgcn_exp2f(fmaf(s0[i + 1], C, mc)); pb += s0[i + 1];
;       }
; #pragma unroll
;       for (int i = 0; i < 16; i += 2) {
;         s1[i] = __builtin_amdgcn_exp2f(fmaf(s1[i], C, mc)); pc += s1[i];
;         s1[i + 1] = __builtin_amdgcn_exp2f(fmaf(s1[i + 1], C, mc)); pd += s1[i + 1];
;       }
;       const float ps = xhalf_sum((pa + pb) + (pc + pd));
;       l_run = l_run * alpha + ps;
;       if (__any(alpha != 1.f)) {
; #pragma unroll
;         for (int d = 0; d < NDV; ++d)
; #pragma unroll
;           for (int i = 0; i < 16; ++i) oacc[d][i] *= alpha;
;       }
	ds_read_b128 v[170:173], v231 offset:24576
	ds_read_b128 v[166:169], v230 offset:24576
	ds_read_b128 v[162:165], v229 offset:24576
	s_nop 15
	v_max3_f32 v202, v82, v83, v84
	s_nop 0
	v_max3_f32 v203, v85, v86, v87
	v_max3_f32 v204, v88, v89, v90
	v_max3_f32 v205, v91, v92, v93
	v_max3_f32 v206, v94, v95, v96
	s_nop 0
	v_max3_f32 v207, v66, v67, v68
	v_max3_f32 v203, v203, v204, v205
	s_nop 0
	v_max3_f32 v202, v97, v81, v202
	v_max3_f32 v208, v69, v70, v71
	v_max3_f32 v209, v72, v73, v74
	v_max3_f32 v210, v75, v76, v77
	v_max3_f32 v211, v78, v79, v80
	s_nop 0
	v_max3_f32 v204, v206, v207, v208
	v_max3_f32 v205, v209, v210, v211
	s_nop 0
	v_max3_f32 v202, v202, v203, v204
	s_nop 0
	v_max3_f32 v202, v202, v205, v205
	s_nop 0
	v_mov_b32_e32 v203, v202
	s_nop 1
	v_permlane32_swap_b32_e32 v202, v203
	v_max3_f32 v220, v248, v202, v203
	v_sub_f32_e32 v202, v248, v220
	v_mov_b32_e32 v248, v220
	v_mul_f32_e32 v220, 0xbdd53b94, v248
	v_fmamk_f32 v82, v82, 0x3dd53b94, v220
	v_mul_f32_e32 v245, 0x3dd53b94, v202
	v_exp_f32_e32 v202, v82
	v_fmamk_f32 v82, v83, 0x3dd53b94, v220
	v_exp_f32_e32 v204, v82
	v_fmamk_f32 v82, v84, 0x3dd53b94, v220
	v_fmamk_f32 v66, v66, 0x3dd53b94, v220
	v_exp_f32_e32 v206, v82
	v_fmamk_f32 v82, v85, 0x3dd53b94, v220
	v_exp_f32_e32 v203, v66
	v_fmamk_f32 v66, v67, 0x3dd53b94, v220
	v_exp_f32_e32 v208, v82
	v_fmamk_f32 v82, v86, 0x3dd53b94, v220
	v_fmamk_f32 v83, v91, 0x3dd53b94, v220
	v_exp_f32_e32 v205, v66
	v_fmamk_f32 v66, v68, 0x3dd53b94, v220
	v_exp_f32_e32 v210, v82
	v_fmamk_f32 v82, v87, 0x3dd53b94, v220
	v_exp_f32_e32 v84, v83
	v_fmamk_f32 v83, v92, 0x3dd53b94, v220
	v_exp_f32_e32 v207, v66
	v_fmamk_f32 v66, v69, 0x3dd53b94, v220
	v_exp_f32_e32 v212, v82
	v_fmamk_f32 v82, v88, 0x3dd53b94, v220
	v_exp_f32_e32 v86, v83
	v_fmamk_f32 v83, v93, 0x3dd53b94, v220
	v_exp_f32_e32 v209, v66
	v_fmamk_f32 v66, v70, 0x3dd53b94, v220
	v_exp_f32_e32 v214, v82
	v_fmamk_f32 v82, v89, 0x3dd53b94, v220
	v_exp_f32_e32 v88, v83
	v_fmamk_f32 v83, v94, 0x3dd53b94, v220
	v_exp_f32_e32 v211, v66
	v_fmamk_f32 v66, v71, 0x3dd53b94, v220
	v_exp_f32_e32 v216, v82
	v_fmamk_f32 v82, v90, 0x3dd53b94, v220
	v_exp_f32_e32 v90, v83
	v_fmamk_f32 v83, v95, 0x3dd53b94, v220
	v_exp_f32_e32 v213, v66
	v_fmamk_f32 v66, v72, 0x3dd53b94, v220
	v_exp_f32_e32 v92, v83
	v_fmamk_f32 v83, v96, 0x3dd53b94, v220
	v_exp_f32_e32 v215, v66
	v_fmamk_f32 v66, v73, 0x3dd53b94, v220
	v_exp_f32_e32 v94, v83
	v_fmamk_f32 v83, v97, 0x3dd53b94, v220
	v_exp_f32_e32 v217, v66
	v_fmamk_f32 v66, v74, 0x3dd53b94, v220
	v_exp_f32_e32 v96, v83
	v_exp_f32_e32 v83, v66
	v_fmamk_f32 v66, v75, 0x3dd53b94, v220
	v_exp_f32_e32 v85, v66
	v_fmamk_f32 v66, v76, 0x3dd53b94, v220
	v_exp_f32_e32 v87, v66
	v_fmamk_f32 v66, v77, 0x3dd53b94, v220
	v_exp_f32_e32 v82, v82
	v_exp_f32_e32 v89, v66
	v_fmamk_f32 v66, v78, 0x3dd53b94, v220
	v_pk_add_f32 v[68:69], v[204:205], 0 op_sel_hi:[1,0]
	v_pk_add_f32 v[70:71], v[202:203], 0 op_sel_hi:[1,0]
	v_exp_f32_e32 v91, v66
	v_fmamk_f32 v66, v79, 0x3dd53b94, v220
	v_pk_add_f32 v[68:69], v[208:209], v[68:69]
	v_pk_add_f32 v[70:71], v[206:207], v[70:71]
	v_exp_f32_e32 v93, v66
	v_fmamk_f32 v66, v80, 0x3dd53b94, v220
	v_fmac_f32_e32 v220, 0x3dd53b94, v81
	v_pk_add_f32 v[68:69], v[212:213], v[68:69]
	v_pk_add_f32 v[70:71], v[210:211], v[70:71]
	v_exp_f32_e32 v95, v66
	v_exp_f32_e32 v97, v220
	v_pk_add_f32 v[68:69], v[216:217], v[68:69]
	v_pk_add_f32 v[70:71], v[214:215], v[70:71]
	v_pk_add_f32 v[68:69], v[84:85], v[68:69]
	v_pk_add_f32 v[70:71], v[82:83], v[70:71]
	v_pk_add_f32 v[68:69], v[88:89], v[68:69]
	v_pk_add_f32 v[70:71], v[86:87], v[70:71]
	v_pk_add_f32 v[68:69], v[92:93], v[68:69]
	v_pk_add_f32 v[70:71], v[90:91], v[70:71]
	v_exp_f32_e32 v66, v245
	v_pk_add_f32 v[68:69], v[96:97], v[68:69]
	v_pk_add_f32 v[70:71], v[94:95], v[70:71]
	v_cmp_neq_f32_e32 vcc, 1.0, v66
	v_pk_add_f32 v[68:69], v[70:71], v[68:69]
	s_nop 0
	v_pk_add_f32 v[68:69], v[68:69], v[68:69] op_sel:[0,1] op_sel_hi:[1,0]
	s_nop 0
	v_mov_b32_e32 v67, v68
	s_nop 1
	v_permlane32_swap_b32_e32 v68, v67
	s_cbranch_vccz .LBB0_362
	v_pk_mul_f32 v[64:65], v[64:65], v[66:67] op_sel_hi:[1,0]
	v_pk_mul_f32 v[62:63], v[62:63], v[66:67] op_sel_hi:[1,0]
	v_pk_mul_f32 v[60:61], v[60:61], v[66:67] op_sel_hi:[1,0]
	v_pk_mul_f32 v[58:59], v[58:59], v[66:67] op_sel_hi:[1,0]
	v_pk_mul_f32 v[56:57], v[56:57], v[66:67] op_sel_hi:[1,0]
	v_pk_mul_f32 v[54:55], v[54:55], v[66:67] op_sel_hi:[1,0]
	v_pk_mul_f32 v[52:53], v[52:53], v[66:67] op_sel_hi:[1,0]
	v_pk_mul_f32 v[50:51], v[50:51], v[66:67] op_sel_hi:[1,0]
	v_pk_mul_f32 v[48:49], v[48:49], v[66:67] op_sel_hi:[1,0]
	v_pk_mul_f32 v[46:47], v[46:47], v[66:67] op_sel_hi:[1,0]
	v_pk_mul_f32 v[44:45], v[44:45], v[66:67] op_sel_hi:[1,0]
	v_pk_mul_f32 v[42:43], v[42:43], v[66:67] op_sel_hi:[1,0]
	v_pk_mul_f32 v[40:41], v[40:41], v[66:67] op_sel_hi:[1,0]
	v_pk_mul_f32 v[38:39], v[38:39], v[66:67] op_sel_hi:[1,0]
	v_pk_mul_f32 v[36:37], v[36:37], v[66:67] op_sel_hi:[1,0]
	v_pk_mul_f32 v[34:35], v[34:35], v[66:67] op_sel_hi:[1,0]
	v_pk_mul_f32 v[32:33], v[32:33], v[66:67] op_sel_hi:[1,0]
	v_pk_mul_f32 v[30:31], v[30:31], v[66:67] op_sel_hi:[1,0]
	v_pk_mul_f32 v[28:29], v[28:29], v[66:67] op_sel_hi:[1,0]
	v_pk_mul_f32 v[26:27], v[26:27], v[66:67] op_sel_hi:[1,0]
	v_pk_mul_f32 v[24:25], v[24:25], v[66:67] op_sel_hi:[1,0]
	v_pk_mul_f32 v[22:23], v[22:23], v[66:67] op_sel_hi:[1,0]
	v_pk_mul_f32 v[20:21], v[20:21], v[66:67] op_sel_hi:[1,0]
	v_pk_mul_f32 v[18:19], v[18:19], v[66:67] op_sel_hi:[1,0]
	v_pk_mul_f32 v[16:17], v[16:17], v[66:67] op_sel_hi:[1,0]
	v_pk_mul_f32 v[14:15], v[14:15], v[66:67] op_sel_hi:[1,0]
	v_pk_mul_f32 v[12:13], v[12:13], v[66:67] op_sel_hi:[1,0]
	v_pk_mul_f32 v[10:11], v[10:11], v[66:67] op_sel_hi:[1,0]
	v_pk_mul_f32 v[8:9], v[8:9], v[66:67] op_sel_hi:[1,0]
	v_pk_mul_f32 v[6:7], v[6:7], v[66:67] op_sel_hi:[1,0]
	v_pk_mul_f32 v[4:5], v[4:5], v[66:67] op_sel_hi:[1,0]
	v_pk_mul_f32 v[2:3], v[2:3], v[66:67] op_sel_hi:[1,0]
; template <int DQK, int DV, int TYPE>
; DI void attn_item(int layer, int qt, int head, char* lds, const Params& P) {
;     ...
;     for (int j = 0; j < NT; ++j) {
;       const int tile = TILE_OF(j);
;       const char* sb = lds + (DB ? (j & 1) * STAGE : 0);
;       constexpr int KD = 2, KRING = 3;
;       bf16x8 kr0[KRING], kr1[KRING];
;     ...
; #pragma unroll
;       for (int s = 0; s < KD; ++s) KFR(s, s)
;       __builtin_amdgcn_sched_barrier(0);
;       if constexpr (DB) {
;         char* sn = lds + ((j + 1) & 1) * STAGE;
;         if (j + 1 < NT) { ATT_SSTORE(sn); }
;         if (j + 2 < NT) { ATT_GLOAD(TILE_OF(j + 2)); }
;       } else {
;         if (j + 1 < NT) { ATT_GLOAD(TILE_OF(j + 1)); }
;       }
;       f32x16 s0, s1;
; #pragma unroll
;       for (int i = 0; i < 16; ++i) { s0[i] = 0.f; s1[i] = 0.f; }
;       {
; #pragma unroll
;         for (int s = 0; s < NS; ++s) {
;           if (s + KD < NS) KFR(s + KD, (s + KD) % KRING)
;           bf16x8 qs;
;           if constexpr (NS > NQR) { if (s < NQR) qs = qf[s < NQR ? s : 0]; else qs = *reinterpret_cast<const bf16x8*>(qpark + (s - NQR) * 4096); }
;           else qs = qf[s];
;           s0 = MFMA(kr0[s % KRING], qs, s0);
;           s1 = MFMA(kr1[s % KRING], qs, s1);
;           __builtin_amdgcn_sched_barrier(0);
;         }
;     ...
;       bf16x8 pf[4];
; #pragma unroll
;       for (int sp = 0; sp < 2; ++sp) {
;         u32x4 w0, w1;
;         w0.x = pk2(s0[8 * sp + 0], s0[8 * sp + 1]); w0.y = pk2(s0[8 * sp + 2], s0[8 * sp + 3]);
;         w0.z = pk2(s0[8 * sp + 4], s0[8 * sp + 5]); w0.w = pk2(s0[8 * sp + 6], s0[8 * sp + 7]);
;         w1.x = pk2(s1[8 * sp + 0], s1[8 * sp + 1]); w1.y = pk2(s1[8 * sp + 2], s1[8 * sp + 3]);
;         w1.z = pk2(s1[8 * sp + 4], s1[8 * sp + 5]); w1.w = pk2(s1[8 * sp + 6], s1[8 * sp + 7]);
;         pf[sp] = __builtin_bit_cast(bf16x8, w0);
;         pf[2 + sp] = __builtin_bit_cast(bf16x8, w1);
;       }
;       {
; #pragma unroll
;         for (int f = 0; f < NDV * 4; ++f) {
;           if (f + VD < NDV * 4) vr[(f + VD) & 7] = VFRAG((f + VD) >> 2, (f + VD) & 3);
;           oacc[f >> 2] = MFMA(vr[f & 7], pf[f & 3], oacc[f >> 2]);
;           __builtin_amdgcn_sched_barrier(0);
;         }
;     ...
;       }
;       __syncthreads();
;       if constexpr (!DB) {
;         if (j + 1 < NT) { ATT_SSTORE(lds); }
;         __syncthreads();
;       }
;     }
.LBB0_362:
	v_add_f32_e32 v245, v68, v67
	v_fmac_f32_e32 v245, v251, v66
	v_cvt_pk_bf16_f32 v66, v202, v204
	v_cvt_pk_bf16_f32 v67, v206, v208
	v_cvt_pk_bf16_f32 v68, v210, v212
	v_cvt_pk_bf16_f32 v69, v214, v216
	v_add_u32_e32 v202, v232, v242
	v_cvt_pk_bf16_f32 v74, v82, v84
	s_waitcnt lgkmcnt(2)
	v_mfma_f32_32x32x16_bf16 v[50:65], v[170:173], v[66:69], v[50:65]
	v_cvt_pk_bf16_f32 v78, v83, v85
	ds_read_b128 v[82:85], v202 offset:24576
	v_cvt_pk_bf16_f32 v70, v203, v205
	v_cvt_pk_bf16_f32 v71, v207, v209
	v_cvt_pk_bf16_f32 v72, v211, v213
	v_cvt_pk_bf16_f32 v73, v215, v217
	v_cvt_pk_bf16_f32 v75, v86, v88
	v_cvt_pk_bf16_f32 v76, v90, v92
	v_cvt_pk_bf16_f32 v77, v94, v96
	v_cvt_pk_bf16_f32 v79, v87, v89
	v_cvt_pk_bf16_f32 v80, v91, v93
	v_cvt_pk_bf16_f32 v81, v95, v97
	s_waitcnt lgkmcnt(2)
	v_mfma_f32_32x32x16_bf16 v[50:65], v[166:169], v[74:77], v[50:65]
	ds_read_b128 v[86:89], v231 offset:28672
	s_waitcnt lgkmcnt(2)
	v_mfma_f32_32x32x16_bf16 v[50:65], v[162:165], v[70:73], v[50:65]
	s_waitcnt vmcnt(4)
	ds_write_b128 v225, v[122:125]
	ds_read_b128 v[90:93], v230 offset:28672
	s_waitcnt lgkmcnt(3)
	v_mfma_f32_32x32x16_bf16 v[50:65], v[82:85], v[78:81], v[50:65]
	ds_write_b128 v225, v[126:129] offset:6144
	ds_read_b128 v[94:97], v229 offset:28672
	s_waitcnt lgkmcnt(4)
	v_mfma_f32_32x32x16_bf16 v[34:49], v[86:89], v[66:69], v[34:49]
	ds_write_b128 v225, v[130:133] offset:12288
	ds_read_b128 v[82:85], v202 offset:28672
	s_waitcnt lgkmcnt(4)
	v_mfma_f32_32x32x16_bf16 v[34:49], v[90:93], v[74:77], v[34:49]
	ds_write_b128 v225, v[134:137] offset:18432
	ds_read_b128 v[86:89], v231 offset:32768
	s_waitcnt lgkmcnt(4)
	v_mfma_f32_32x32x16_bf16 v[34:49], v[94:97], v[70:73], v[34:49]
	ds_write_b128 v226, v[138:141]
	ds_read_b128 v[90:93], v230 offset:32768
	s_waitcnt lgkmcnt(4)
	v_mfma_f32_32x32x16_bf16 v[34:49], v[82:85], v[78:81], v[34:49]
	ds_write_b128 v226, v[142:145] offset:12288
	ds_read_b128 v[94:97], v229 offset:32768
	s_waitcnt lgkmcnt(4)
	v_mfma_f32_32x32x16_bf16 v[18:33], v[86:89], v[66:69], v[18:33]
	ds_read_b128 v[82:85], v202 offset:32768
	s_waitcnt lgkmcnt(3)
	v_mfma_f32_32x32x16_bf16 v[18:33], v[90:93], v[74:77], v[18:33]
	ds_read_b128 v[86:89], v231 offset:36864
	s_waitcnt lgkmcnt(2)
	v_mfma_f32_32x32x16_bf16 v[18:33], v[94:97], v[70:73], v[18:33]
	ds_read_b128 v[90:93], v230 offset:36864
	s_waitcnt lgkmcnt(2)
	v_mfma_f32_32x32x16_bf16 v[18:33], v[82:85], v[78:81], v[18:33]
	ds_read_b128 v[94:97], v229 offset:36864
	s_waitcnt lgkmcnt(2)
	v_mfma_f32_32x32x16_bf16 v[2:17], v[86:89], v[66:69], v[2:17]
	ds_read_b128 v[82:85], v202 offset:36864
	s_waitcnt lgkmcnt(2)
	v_mfma_f32_32x32x16_bf16 v[2:17], v[90:93], v[74:77], v[2:17]
	s_waitcnt lgkmcnt(1)
	v_mfma_f32_32x32x16_bf16 v[2:17], v[94:97], v[70:73], v[2:17]
	s_waitcnt lgkmcnt(0)
	v_mfma_f32_32x32x16_bf16 v[2:17], v[82:85], v[78:81], v[2:17]
	s_add_u32 s0, s0, 0x2000
	s_addc_u32 s1, s1, 0
	s_add_u32 s44, s44, 0x80
	s_addc_u32 s45, s45, 0
	s_add_u32 s46, s46, 0x20000
	s_addc_u32 s47, s47, 0
	s_cmp_eq_u32 s0, 0x206000
	s_waitcnt lgkmcnt(0)
	s_barrier
	s_cbranch_scc1 .LBB0_364
	v_mov_b32_e32 v251, v245
	s_branch .LBB0_360
.LBB0_364:
	ds_read_b128 v[66:69], v246
	ds_read_b128 v[70:73], v246 offset:12288
	ds_read_b128 v[122:125], v247
	ds_read_b128 v[126:129], v247 offset:12288
	s_waitcnt lgkmcnt(3)
	v_mfma_f32_32x32x16_bf16 v[82:97], v[66:69], v[118:121], 0
	ds_read_b128 v[130:133], v249
	ds_read_b128 v[134:137], v249 offset:12288
	s_waitcnt lgkmcnt(4)
	v_mfma_f32_32x32x16_bf16 v[66:81], v[70:73], v[118:121], 0
	s_waitcnt vmcnt(0)
	ds_write_b128 v227, v[146:149] offset:24576
	s_waitcnt lgkmcnt(4)
	v_mfma_f32_32x32x16_bf16 v[82:97], v[122:125], v[114:117], v[82:97]
	ds_read_b128 v[118:121], v250
	ds_read_b128 v[122:125], v250 offset:12288
	s_waitcnt lgkmcnt(5)
	v_mfma_f32_32x32x16_bf16 v[66:81], v[126:129], v[114:117], v[66:81]
	ds_write_b128 v227, v[150:153] offset:28672
	s_waitcnt lgkmcnt(5)
	v_mfma_f32_32x32x16_bf16 v[82:97], v[130:133], v[110:113], v[82:97]
	ds_read_b128 v[114:117], v244
	ds_read_b128 v[126:129], v244 offset:12288
	s_waitcnt lgkmcnt(6)
	v_mfma_f32_32x32x16_bf16 v[66:81], v[134:137], v[110:113], v[66:81]
	ds_write_b128 v227, v[154:157] offset:32768
	s_waitcnt lgkmcnt(5)
	v_mfma_f32_32x32x16_bf16 v[82:97], v[118:121], v[106:109], v[82:97]
	ds_read_b128 v[110:113], v243
	ds_read_b128 v[118:121], v243 offset:12288
	s_waitcnt lgkmcnt(6)
	v_mfma_f32_32x32x16_bf16 v[66:81], v[122:125], v[106:109], v[66:81]
	ds_write_b128 v227, v[158:161] offset:36864
	s_waitcnt lgkmcnt(5)
	v_mfma_f32_32x32x16_bf16 v[82:97], v[114:117], v[102:105], v[82:97]
	ds_read_b128 v[106:109], v238
	ds_read_b128 v[114:117], v238 offset:12288
	s_waitcnt lgkmcnt(6)
	v_mfma_f32_32x32x16_bf16 v[66:81], v[126:129], v[102:105], v[66:81]
	s_waitcnt lgkmcnt(4)
	v_mfma_f32_32x32x16_bf16 v[82:97], v[110:113], v[98:101], v[82:97]
	ds_read_b128 v[102:105], v237
	ds_read_b128 v[110:113], v237 offset:12288
	s_waitcnt lgkmcnt(5)
	v_mfma_f32_32x32x16_bf16 v[66:81], v[118:121], v[98:101], v[66:81]
	ds_read_b128 v[98:101], v194 offset:40960
	ds_read_b128 v[118:121], v236
	s_waitcnt lgkmcnt(1)
	v_mfma_f32_32x32x16_bf16 v[82:97], v[106:109], v[98:101], v[82:97]
	ds_read_b128 v[106:109], v236 offset:12288
	v_mfma_f32_32x32x16_bf16 v[66:81], v[114:117], v[98:101], v[66:81]
	ds_read_b128 v[98:101], v194 offset:45056
	ds_read_b128 v[114:117], v235
	s_waitcnt lgkmcnt(1)
	v_mfma_f32_32x32x16_bf16 v[82:97], v[102:105], v[98:101], v[82:97]
	ds_read_b128 v[102:105], v235 offset:12288
	v_mfma_f32_32x32x16_bf16 v[66:81], v[110:113], v[98:101], v[66:81]
	ds_read_b128 v[98:101], v194 offset:49152
	ds_read_b128 v[110:113], v234
	s_waitcnt lgkmcnt(1)
	v_mfma_f32_32x32x16_bf16 v[82:97], v[118:121], v[98:101], v[82:97]
	ds_read_b128 v[118:121], v234 offset:12288
	v_mfma_f32_32x32x16_bf16 v[66:81], v[106:109], v[98:101], v[66:81]
	ds_read_b128 v[98:101], v194 offset:53248
	ds_read_b128 v[106:109], v233
	s_waitcnt lgkmcnt(1)
	v_mfma_f32_32x32x16_bf16 v[82:97], v[114:117], v[98:101], v[82:97]
	ds_read_b128 v[114:117], v233 offset:12288
	v_mfma_f32_32x32x16_bf16 v[66:81], v[102:105], v[98:101], v[66:81]
	ds_read_b128 v[98:101], v194 offset:57344
	s_waitcnt lgkmcnt(0)
	v_mfma_f32_32x32x16_bf16 v[82:97], v[110:113], v[98:101], v[82:97]
	v_mfma_f32_32x32x16_bf16 v[66:81], v[118:121], v[98:101], v[66:81]
	ds_read_b128 v[110:113], v194 offset:61440
	s_waitcnt lgkmcnt(0)
	v_mfma_f32_32x32x16_bf16 v[82:97], v[106:109], v[110:113], v[82:97]
	v_mfma_f32_32x32x16_bf16 v[66:81], v[114:117], v[110:113], v[66:81]
	s_barrier
; template <int DQK, int DV, int TYPE>
; DI void attn_item(int layer, int qt, int head, char* lds, const Params& P) {
;     ...
;       const char* vb0 = sb + VOFF + r * 128;
;     ...
;       constexpr int VD = 3;
;       bf16x8 vr[8];
; #pragma unroll
;       for (int g = 0; g < VD; ++g) vr[g] = VFRAG(g >> 2, g & 3);
;       if (TYPE == 2 && latent && j < na) {
;         const int kb0 = tile * 64 - qrow;
; #pragma unroll
;         for (int i = 0; i < 16; ++i) {
;           const int d0 = kb0 + crow(i, h), d1 = d0 + 32;
;           if (d0 > 128 || d0 < -128) s0[i] = -1e30f;
;           if (d1 > 128 || d1 < -128) s1[i] = -1e30f;
;         }
;       }
;       const float tm0 = vmax3w(s0[0], s0[1], s0[2], s1[0]);
;       const float tm1 = vmax3d(s0[3], s0[4], s0[5], tm0), tm2 = vmax3d(s0[6], s0[7], s0[8], tm0), tm3 = vmax3d(s0[9], s0[10], s0[11], tm0);
;       const float tm4 = vmax3d(s0[12], s0[13], s0[14], tm0);
;       const float tm5 = vmax3d4(s1[0], s1[1], s1[2], tm1, tm2, tm3, tm4), tm6 = vmax3d(s1[3], s1[4], s1[5], tm5), tm7 = vmax3d(s1[6], s1[7], s1[8], tm5);
;       const float tm8 = vmax3d(s1[9], s1[10], s1[11], tm5), tm9 = vmax3d(s1[12], s1[13], s1[14], tm5), tma = vmax3d(s0[15], s1[15], tm0, tm5), tmb = vmax3(tm1, tm2, tm3);
;       const float tmc = vmax3(tm4, tm5, tm6), tmd = vmax3(tm7, tm8, tm9);
;       float tmax = xhalf_max(vmax3(vmax3(tma, tmb, tmc), tmd, tmd));
;       const float mnew = fmaxf(m_run, tmax);
;       const float alpha = __builtin_amdgcn_exp2f((m_run - mnew) * C);
;       m_run = mnew;
;       const float mc = -mnew * C;
;       float pa = 0.f, pb = 0.f, pc = 0.f, pd = 0.f;
; #pragma unroll
;       for (int i = 0; i < 16; i += 2) {
;         s0[i] = __builtin_amdgcn_exp2f(fmaf(s0[i], C, mc)); pa += s0[i];
;         s0[i + 1] = __builtin_amdgcn_exp2f(fmaf(s0[i + 1], C, mc)); pb += s0[i + 1];
;       }
; #pragma unroll
;       for (int i = 0; i < 16; i += 2) {
;         s1[i] = __builtin_amdgcn_exp2f(fmaf(s1[i], C, mc)); pc += s1[i];
;         s1[i + 1] = __builtin_amdgcn_exp2f(fmaf(s1[i + 1], C, mc)); pd += s1[i + 1];
;       }
;       const float ps = xhalf_sum((pa + pb) + (pc + pd));
;       l_run = l_run * alpha + ps;
;       if (__any(alpha != 1.f)) {
; #pragma unroll
;         for (int d = 0; d < NDV; ++d)
; #pragma unroll
;           for (int i = 0; i < 16; ++i) oacc[d][i] *= alpha;
;       }
	ds_read_b128 v[106:109], v231 offset:24576
	ds_read_b128 v[102:105], v230 offset:24576
	ds_read_b128 v[98:101], v229 offset:24576
	s_nop 15
	v_max3_f32 v0, v82, v83, v84
	s_nop 0
	v_max3_f32 v110, v85, v86, v87
	v_max3_f32 v111, v88, v89, v90
	v_max3_f32 v112, v91, v92, v93
	v_max3_f32 v113, v94, v95, v96
	s_nop 0
	v_max3_f32 v114, v66, v67, v68
	v_max3_f32 v110, v110, v111, v112
	s_nop 0
	v_max3_f32 v0, v97, v81, v0
	v_max3_f32 v115, v69, v70, v71
	v_max3_f32 v116, v72, v73, v74
	v_max3_f32 v117, v75, v76, v77
	v_max3_f32 v118, v78, v79, v80
	s_nop 0
	v_max3_f32 v111, v113, v114, v115
	v_max3_f32 v112, v116, v117, v118
	s_nop 0
	v_max3_f32 v0, v0, v110, v111
	s_nop 0
	v_max3_f32 v0, v0, v112, v112
	s_nop 0
	v_mov_b32_e32 v110, v0
	s_nop 1
	v_permlane32_swap_b32_e32 v0, v110
	v_max3_f32 v0, v248, v0, v110
	v_sub_f32_e32 v110, v248, v0
	v_mul_f32_e32 v0, 0xbdd53b94, v0
	v_mul_f32_e32 v115, 0x3dd53b94, v110
	v_fmamk_f32 v110, v82, 0x3dd53b94, v0
	v_fmamk_f32 v82, v83, 0x3dd53b94, v0
	v_exp_f32_e32 v82, v82
	v_fmamk_f32 v85, v85, 0x3dd53b94, v0
	v_exp_f32_e32 v85, v85
	v_exp_f32_e32 v83, v110
	v_add_f32_e32 v110, 0, v82
	v_fmamk_f32 v88, v88, 0x3dd53b94, v0
	v_add_f32_e32 v111, v85, v110
	v_fmamk_f32 v110, v86, 0x3dd53b94, v0
	v_fmamk_f32 v86, v87, 0x3dd53b94, v0
	v_exp_f32_e32 v86, v86
	v_fmamk_f32 v87, v89, 0x3dd53b94, v0
	v_exp_f32_e32 v89, v87
	v_fmamk_f32 v66, v66, 0x3dd53b94, v0
	v_add_f32_e32 v87, v86, v111
	v_exp_f32_e32 v111, v88
	v_add_f32_e32 v112, v89, v87
	v_fmamk_f32 v87, v91, 0x3dd53b94, v0
	v_fmamk_f32 v88, v90, 0x3dd53b94, v0
	v_exp_f32_e32 v87, v87
	v_fmamk_f32 v90, v93, 0x3dd53b94, v0
	v_exp_f32_e32 v90, v90
	v_fmamk_f32 v91, v92, 0x3dd53b94, v0
	v_add_f32_e32 v93, v87, v112
	v_fmamk_f32 v92, v95, 0x3dd53b94, v0
	v_add_f32_e32 v112, v90, v93
	v_fmamk_f32 v93, v94, 0x3dd53b94, v0
	v_exp_f32_e32 v92, v92
	v_fmamk_f32 v94, v97, 0x3dd53b94, v0
	v_exp_f32_e32 v94, v94
	v_fmamk_f32 v95, v96, 0x3dd53b94, v0
	v_add_f32_e32 v97, v92, v112
	v_exp_f32_e32 v96, v66
	v_fmamk_f32 v66, v67, 0x3dd53b94, v0
	v_add_f32_e32 v116, v94, v97
	v_exp_f32_e32 v97, v66
	v_fmamk_f32 v66, v68, 0x3dd53b94, v0
	v_fmamk_f32 v71, v71, 0x3dd53b94, v0
	v_exp_f32_e32 v68, v66
	v_fmamk_f32 v66, v69, 0x3dd53b94, v0
	v_fmamk_f32 v70, v70, 0x3dd53b94, v0
	v_exp_f32_e32 v112, v71
	v_fmamk_f32 v71, v72, 0x3dd53b94, v0
	v_exp_f32_e32 v69, v66
	v_exp_f32_e32 v70, v70
	v_exp_f32_e32 v113, v71
	v_fmamk_f32 v71, v73, 0x3dd53b94, v0
	v_exp_f32_e32 v114, v71
	v_fmamk_f32 v71, v74, 0x3dd53b94, v0
	v_add_f32_e32 v66, 0, v96
	v_exp_f32_e32 v71, v71
	v_fmamk_f32 v72, v75, 0x3dd53b94, v0
	v_fmamk_f32 v73, v76, 0x3dd53b94, v0
	v_add_f32_e32 v67, 0, v97
	v_add_f32_e32 v66, v68, v66
	v_exp_f32_e32 v72, v72
	v_exp_f32_e32 v73, v73
	v_fmamk_f32 v74, v77, 0x3dd53b94, v0
	v_fmamk_f32 v75, v78, 0x3dd53b94, v0
	v_add_f32_e32 v67, v69, v67
	v_add_f32_e32 v66, v70, v66
	v_exp_f32_e32 v74, v74
	v_exp_f32_e32 v75, v75
	v_fmamk_f32 v76, v79, 0x3dd53b94, v0
	v_fmamk_f32 v77, v80, 0x3dd53b94, v0
	v_fmamk_f32 v84, v84, 0x3dd53b94, v0
	v_add_f32_e32 v67, v112, v67
	v_add_f32_e32 v66, v113, v66
	v_exp_f32_e32 v76, v76
	v_exp_f32_e32 v77, v77
	v_exp_f32_e32 v84, v84
	v_add_f32_e32 v67, v114, v67
	v_add_f32_e32 v66, v71, v66
	v_exp_f32_e32 v110, v110
	v_add_f32_e32 v67, v72, v67
	v_add_f32_e32 v66, v73, v66
	v_fmac_f32_e32 v0, 0x3dd53b94, v81
	v_add_f32_e32 v67, v74, v67
	v_exp_f32_e32 v78, v0
	v_add_f32_e32 v0, v75, v66
	v_exp_f32_e32 v88, v88
	v_add_f32_e32 v66, v76, v67
	v_add_f32_e32 v67, v77, v0
	v_add_f32_e32 v0, 0, v83
	v_exp_f32_e32 v91, v91
	v_add_f32_e32 v0, v84, v0
	v_exp_f32_e32 v93, v93
	v_add_f32_e32 v0, v110, v0
	v_exp_f32_e32 v95, v95
	v_add_f32_e32 v0, v111, v0
	v_add_f32_e32 v0, v88, v0
	v_add_f32_e32 v0, v91, v0
	v_add_f32_e32 v0, v93, v0
	v_add_f32_e32 v66, v78, v66
	v_add_f32_e32 v79, v95, v0
	v_exp_f32_e32 v0, v115
	v_add_f32_e32 v79, v79, v116
	v_add_f32_e32 v66, v67, v66
	v_add_f32_e32 v66, v79, v66
	v_mov_b32_e32 v67, v66
	s_nop 1
	v_permlane32_swap_b32_e32 v66, v67
	v_cmp_neq_f32_e32 vcc, 1.0, v0
	s_cbranch_vccz .LBB0_366
	v_pk_mul_f32 v[64:65], v[64:65], v[0:1] op_sel_hi:[1,0]
	v_pk_mul_f32 v[62:63], v[62:63], v[0:1] op_sel_hi:[1,0]
	v_pk_mul_f32 v[60:61], v[60:61], v[0:1] op_sel_hi:[1,0]
	v_pk_mul_f32 v[58:59], v[58:59], v[0:1] op_sel_hi:[1,0]
	v_pk_mul_f32 v[56:57], v[56:57], v[0:1] op_sel_hi:[1,0]
	v_pk_mul_f32 v[54:55], v[54:55], v[0:1] op_sel_hi:[1,0]
	v_pk_mul_f32 v[52:53], v[52:53], v[0:1] op_sel_hi:[1,0]
	v_pk_mul_f32 v[50:51], v[50:51], v[0:1] op_sel_hi:[1,0]
	v_pk_mul_f32 v[48:49], v[48:49], v[0:1] op_sel_hi:[1,0]
	v_pk_mul_f32 v[46:47], v[46:47], v[0:1] op_sel_hi:[1,0]
	v_pk_mul_f32 v[44:45], v[44:45], v[0:1] op_sel_hi:[1,0]
	v_pk_mul_f32 v[42:43], v[42:43], v[0:1] op_sel_hi:[1,0]
	v_pk_mul_f32 v[40:41], v[40:41], v[0:1] op_sel_hi:[1,0]
	v_pk_mul_f32 v[38:39], v[38:39], v[0:1] op_sel_hi:[1,0]
	v_pk_mul_f32 v[36:37], v[36:37], v[0:1] op_sel_hi:[1,0]
	v_pk_mul_f32 v[34:35], v[34:35], v[0:1] op_sel_hi:[1,0]
	v_pk_mul_f32 v[32:33], v[32:33], v[0:1] op_sel_hi:[1,0]
	v_pk_mul_f32 v[30:31], v[30:31], v[0:1] op_sel_hi:[1,0]
	v_pk_mul_f32 v[28:29], v[28:29], v[0:1] op_sel_hi:[1,0]
	v_pk_mul_f32 v[26:27], v[26:27], v[0:1] op_sel_hi:[1,0]
	v_pk_mul_f32 v[24:25], v[24:25], v[0:1] op_sel_hi:[1,0]
	v_pk_mul_f32 v[22:23], v[22:23], v[0:1] op_sel_hi:[1,0]
	v_pk_mul_f32 v[20:21], v[20:21], v[0:1] op_sel_hi:[1,0]
	v_pk_mul_f32 v[18:19], v[18:19], v[0:1] op_sel_hi:[1,0]
	v_pk_mul_f32 v[16:17], v[16:17], v[0:1] op_sel_hi:[1,0]
	v_pk_mul_f32 v[14:15], v[14:15], v[0:1] op_sel_hi:[1,0]
	v_pk_mul_f32 v[12:13], v[12:13], v[0:1] op_sel_hi:[1,0]
	v_pk_mul_f32 v[10:11], v[10:11], v[0:1] op_sel_hi:[1,0]
	v_pk_mul_f32 v[8:9], v[8:9], v[0:1] op_sel_hi:[1,0]
	v_pk_mul_f32 v[6:7], v[6:7], v[0:1] op_sel_hi:[1,0]
	v_pk_mul_f32 v[4:5], v[4:5], v[0:1] op_sel_hi:[1,0]
	v_pk_mul_f32 v[2:3], v[2:3], v[0:1] op_sel_hi:[1,0]
